# G1 epilogue stores in scalar-base form (lane offset + scalar base advanced per row group; one s_nop 1 keeps the 2 wait states before a store's data registers are rewritten); stacked on stack33
# speedup vs baseline: 1.0067x; 1.0059x over previous
; __device__ __forceinline__ unsigned cvt_pk_bf16(float lo, float hi) { unsigned r; asm volatile("v_cvt_pk_bf16_f32 %0, %1, %2" : "=v"(r) : "v"(lo), "v"(hi)); return r; }
; #define x (arg_in(0))
;     __device__ __forceinline__ void operator()(const f32x4 (&acc)[2][2][4][2], const Unit& u, int wr, int wc, int fr, int fq) const {
;         const int row0 = u.pm * BM + wr * 64 + fr, col0 = u.pn * BM + wc * 32 + 8 * fq;
;         const float sc = u.pn < 2 ? qscale : 1.f;
; #pragma unroll
;         for (int ai = 0; ai < 2; ++ai)
; #pragma unroll
;             for (int m = 0; m < 4; ++m) { bf16_t* rowp = O + (size_t)(u.pm >> 4) * bpad + (size_t)(row0 + ai * HALF + m * 16) * ldc + col0;
; #pragma unroll
;                 for (int bj = 0; bj < 2; ++bj) { const f32x4 v0 = acc[ai][bj][m][0] * sc, v1 = acc[ai][bj][m][1] * sc;
;                     u32x4 w; w.x = cvt_pk_bf16(v0[0], v0[1]); w.y = cvt_pk_bf16(v0[2], v0[3]); w.z = cvt_pk_bf16(v1[0], v1[1]); w.w = cvt_pk_bf16(v1[2], v1[3]);
;                     *(u32x4*)(rowp + bj * HALF) = w; } }
.LBB0_167:
	s_cmp_lt_i32 s70, 2
	s_cselect_b64 vcc, -1, 0
	s_ashr_i32 s36, s88, 4
	s_ashr_i32 s37, s36, 31
	s_lshl_b64 s[36:37], s[36:37], 21
	s_add_u32 s36, s23, s36
	s_addc_u32 s37, s25, s37
	s_mul_i32 s98, s88, 0x140000
	s_lshl_b32 s99, s70, 9
	s_add_u32 s98, s98, s99
	s_add_u32 s98, s36, s98
	s_addc_u32 s99, s37, 0
	v_mul_u32_u24_e32 v149, 0x1400, v141
	v_lshl_add_u32 v149, v147, 1, v149
	v_mov_b32_e32 v140, 0x3e8293ee
	v_cndmask_b32_e32 v140, 1.0, v140, vcc
	v_pk_mul_f32 v[150:151], v[140:141], v[124:125] op_sel_hi:[0,1]
	v_pk_mul_f32 v[152:153], v[140:141], v[126:127] op_sel_hi:[0,1]
	v_cvt_pk_bf16_f32 v150, v150, v151
	v_cvt_pk_bf16_f32 v151, v152, v153
	v_pk_mul_f32 v[156:157], v[140:141], v[122:123] op_sel_hi:[0,1]
	v_pk_mul_f32 v[158:159], v[140:141], v[120:121] op_sel_hi:[0,1]
	v_cvt_pk_bf16_f32 v152, v158, v159
	v_cvt_pk_bf16_f32 v153, v156, v157
	global_store_dwordx4 v149, v[150:153], s[98:99]
	v_pk_mul_f32 v[156:157], v[140:141], v[90:91] op_sel_hi:[0,1]
	v_pk_mul_f32 v[158:159], v[140:141], v[88:89] op_sel_hi:[0,1]
	v_pk_mul_f32 v[150:151], v[140:141], v[92:93] op_sel_hi:[0,1]
	v_pk_mul_f32 v[152:153], v[140:141], v[94:95] op_sel_hi:[0,1]
	v_cvt_pk_bf16_f32 v150, v150, v151
	v_cvt_pk_bf16_f32 v151, v152, v153
	v_cvt_pk_bf16_f32 v152, v158, v159
	v_cvt_pk_bf16_f32 v153, v156, v157
	global_store_dwordx4 v149, v[150:153], s[98:99] offset:256
	s_add_u32 s98, s98, 0x14000
	s_addc_u32 s99, s99, 0
	v_pk_mul_f32 v[156:157], v[140:141], v[114:115] op_sel_hi:[0,1]
	v_pk_mul_f32 v[158:159], v[140:141], v[112:113] op_sel_hi:[0,1]
	v_pk_mul_f32 v[150:151], v[140:141], v[116:117] op_sel_hi:[0,1]
	v_pk_mul_f32 v[152:153], v[140:141], v[118:119] op_sel_hi:[0,1]
	v_cvt_pk_bf16_f32 v150, v150, v151
	v_cvt_pk_bf16_f32 v151, v152, v153
	v_cvt_pk_bf16_f32 v152, v158, v159
	v_cvt_pk_bf16_f32 v153, v156, v157
	global_store_dwordx4 v149, v[150:153], s[98:99]
	v_pk_mul_f32 v[156:157], v[140:141], v[82:83] op_sel_hi:[0,1]
	v_pk_mul_f32 v[158:159], v[140:141], v[80:81] op_sel_hi:[0,1]
	v_pk_mul_f32 v[150:151], v[140:141], v[84:85] op_sel_hi:[0,1]
	v_pk_mul_f32 v[152:153], v[140:141], v[86:87] op_sel_hi:[0,1]
	v_cvt_pk_bf16_f32 v150, v150, v151
	v_cvt_pk_bf16_f32 v151, v152, v153
	v_cvt_pk_bf16_f32 v152, v158, v159
	v_cvt_pk_bf16_f32 v153, v156, v157
	global_store_dwordx4 v149, v[150:153], s[98:99] offset:256
	s_add_u32 s98, s98, 0x14000
	s_addc_u32 s99, s99, 0
	v_pk_mul_f32 v[156:157], v[140:141], v[106:107] op_sel_hi:[0,1]
	v_pk_mul_f32 v[158:159], v[140:141], v[104:105] op_sel_hi:[0,1]
	v_pk_mul_f32 v[150:151], v[140:141], v[108:109] op_sel_hi:[0,1]
	v_pk_mul_f32 v[152:153], v[140:141], v[110:111] op_sel_hi:[0,1]
	v_cvt_pk_bf16_f32 v150, v150, v151
	v_cvt_pk_bf16_f32 v151, v152, v153
	v_cvt_pk_bf16_f32 v152, v158, v159
	v_cvt_pk_bf16_f32 v153, v156, v157
	global_store_dwordx4 v149, v[150:153], s[98:99]
	v_pk_mul_f32 v[156:157], v[140:141], v[74:75] op_sel_hi:[0,1]
	v_pk_mul_f32 v[158:159], v[140:141], v[72:73] op_sel_hi:[0,1]
	v_pk_mul_f32 v[150:151], v[140:141], v[76:77] op_sel_hi:[0,1]
	v_pk_mul_f32 v[152:153], v[140:141], v[78:79] op_sel_hi:[0,1]
	v_cvt_pk_bf16_f32 v150, v150, v151
	v_cvt_pk_bf16_f32 v151, v152, v153
	v_cvt_pk_bf16_f32 v152, v158, v159
	v_cvt_pk_bf16_f32 v153, v156, v157
	global_store_dwordx4 v149, v[150:153], s[98:99] offset:256
	s_add_u32 s98, s98, 0x14000
	s_addc_u32 s99, s99, 0
	v_pk_mul_f32 v[156:157], v[140:141], v[98:99] op_sel_hi:[0,1]
	v_pk_mul_f32 v[158:159], v[140:141], v[96:97] op_sel_hi:[0,1]
	v_pk_mul_f32 v[150:151], v[140:141], v[100:101] op_sel_hi:[0,1]
	v_pk_mul_f32 v[152:153], v[140:141], v[102:103] op_sel_hi:[0,1]
	v_cvt_pk_bf16_f32 v150, v150, v151
	v_cvt_pk_bf16_f32 v151, v152, v153
	v_cvt_pk_bf16_f32 v152, v158, v159
	v_cvt_pk_bf16_f32 v153, v156, v157
	global_store_dwordx4 v149, v[150:153], s[98:99]
	v_pk_mul_f32 v[156:157], v[140:141], v[66:67] op_sel_hi:[0,1]
	v_pk_mul_f32 v[158:159], v[140:141], v[64:65] op_sel_hi:[0,1]
	v_pk_mul_f32 v[150:151], v[140:141], v[68:69] op_sel_hi:[0,1]
	v_pk_mul_f32 v[152:153], v[140:141], v[70:71] op_sel_hi:[0,1]
	v_cvt_pk_bf16_f32 v150, v150, v151
	v_cvt_pk_bf16_f32 v151, v152, v153
	v_cvt_pk_bf16_f32 v152, v158, v159
	v_cvt_pk_bf16_f32 v153, v156, v157
	global_store_dwordx4 v149, v[150:153], s[98:99] offset:256
	s_add_u32 s98, s98, 0x64000
	s_addc_u32 s99, s99, 0
	v_pk_mul_f32 v[156:157], v[140:141], v[58:59] op_sel_hi:[0,1]
	v_pk_mul_f32 v[158:159], v[140:141], v[56:57] op_sel_hi:[0,1]
	v_pk_mul_f32 v[150:151], v[140:141], v[60:61] op_sel_hi:[0,1]
	v_pk_mul_f32 v[152:153], v[140:141], v[62:63] op_sel_hi:[0,1]
	v_cvt_pk_bf16_f32 v150, v150, v151
	v_cvt_pk_bf16_f32 v151, v152, v153
	v_cvt_pk_bf16_f32 v152, v158, v159
	v_cvt_pk_bf16_f32 v153, v156, v157
	global_store_dwordx4 v149, v[150:153], s[98:99]
	v_pk_mul_f32 v[156:157], v[140:141], v[26:27] op_sel_hi:[0,1]
	v_pk_mul_f32 v[158:159], v[140:141], v[24:25] op_sel_hi:[0,1]
	v_pk_mul_f32 v[150:151], v[140:141], v[28:29] op_sel_hi:[0,1]
	v_pk_mul_f32 v[152:153], v[140:141], v[30:31] op_sel_hi:[0,1]
	v_cvt_pk_bf16_f32 v150, v150, v151
	v_cvt_pk_bf16_f32 v151, v152, v153
	v_cvt_pk_bf16_f32 v152, v158, v159
	v_cvt_pk_bf16_f32 v153, v156, v157
	global_store_dwordx4 v149, v[150:153], s[98:99] offset:256
	s_add_u32 s98, s98, 0x14000
	s_addc_u32 s99, s99, 0
	v_pk_mul_f32 v[156:157], v[140:141], v[50:51] op_sel_hi:[0,1]
	v_pk_mul_f32 v[158:159], v[140:141], v[48:49] op_sel_hi:[0,1]
	v_pk_mul_f32 v[150:151], v[140:141], v[52:53] op_sel_hi:[0,1]
	v_pk_mul_f32 v[152:153], v[140:141], v[54:55] op_sel_hi:[0,1]
	v_cvt_pk_bf16_f32 v150, v150, v151
	v_cvt_pk_bf16_f32 v151, v152, v153
	v_cvt_pk_bf16_f32 v152, v158, v159
; __device__ __forceinline__ unsigned cvt_pk_bf16(float lo, float hi) { unsigned r; asm volatile("v_cvt_pk_bf16_f32 %0, %1, %2" : "=v"(r) : "v"(lo), "v"(hi)); return r; }
; #define x (arg_in(0))
;     __device__ __forceinline__ void operator()(const f32x4 (&acc)[2][2][4][2], const Unit& u, int wr, int wc, int fr, int fq) const {
;     ...
;             for (int m = 0; m < 4; ++m) { bf16_t* rowp = O + (size_t)(u.pm >> 4) * bpad + (size_t)(row0 + ai * HALF + m * 16) * ldc + col0;
; #pragma unroll
;                 for (int bj = 0; bj < 2; ++bj) { const f32x4 v0 = acc[ai][bj][m][0] * sc, v1 = acc[ai][bj][m][1] * sc;
;                     u32x4 w; w.x = cvt_pk_bf16(v0[0], v0[1]); w.y = cvt_pk_bf16(v0[2], v0[3]); w.z = cvt_pk_bf16(v1[0], v1[1]); w.w = cvt_pk_bf16(v1[2], v1[3]);
;                     *(u32x4*)(rowp + bj * HALF) = w; } }
;         if (u.pn == 2 || u.pn == 3) {
; #pragma unroll
;             for (int ai = 0; ai < 2; ++ai)
; #pragma unroll
;                 for (int bj = 0; bj < 2; ++bj) { float mx = 0.f;
; #pragma unroll
;                     for (int m = 0; m < 4; ++m) { const f32x4 a = acc[ai][bj][m][0], b = acc[ai][bj][m][1];
;                         float ss = (a[0] * a[0] + a[1] * a[1]) + (a[2] * a[2] + a[3] * a[3]) + (b[0] * b[0] + b[1] * b[1]) + (b[2] * b[2] + b[3] * b[3]);
;                         ss += __shfl_xor(ss, 16); ss += __shfl_xor(ss, 32); mx = fmaxf(mx, ss); }
;                     mx = fmaxf(mx, __shfl_xor(mx, 1)); mx = fmaxf(mx, __shfl_xor(mx, 2)); mx = fmaxf(mx, __shfl_xor(mx, 4)); mx = fmaxf(mx, __shfl_xor(mx, 8));
;                     if (fr == 0 && fq == 0) { const int b = u.pm >> 4, tile = (u.pm * 4 + ai * 2 + wr) & 63, head = (u.pn - 2) * 4 + bj * 2 + (wc >> 1), half = wc & 1;
;                         atomicMax(kn2 + ((b * 8 + head) * 2 + half) * 64 + tile, __float_as_uint(mx)); } }
	v_cvt_pk_bf16_f32 v153, v156, v157
	global_store_dwordx4 v149, v[150:153], s[98:99]
	v_pk_mul_f32 v[156:157], v[140:141], v[18:19] op_sel_hi:[0,1]
	v_pk_mul_f32 v[158:159], v[140:141], v[16:17] op_sel_hi:[0,1]
	v_pk_mul_f32 v[150:151], v[140:141], v[20:21] op_sel_hi:[0,1]
	v_pk_mul_f32 v[152:153], v[140:141], v[22:23] op_sel_hi:[0,1]
	v_cvt_pk_bf16_f32 v150, v150, v151
	v_cvt_pk_bf16_f32 v151, v152, v153
	v_cvt_pk_bf16_f32 v152, v158, v159
	v_cvt_pk_bf16_f32 v153, v156, v157
	global_store_dwordx4 v149, v[150:153], s[98:99] offset:256
	s_add_u32 s98, s98, 0x14000
	s_addc_u32 s99, s99, 0
	v_pk_mul_f32 v[156:157], v[140:141], v[42:43] op_sel_hi:[0,1]
	v_pk_mul_f32 v[158:159], v[140:141], v[40:41] op_sel_hi:[0,1]
	v_pk_mul_f32 v[150:151], v[140:141], v[44:45] op_sel_hi:[0,1]
	v_pk_mul_f32 v[152:153], v[140:141], v[46:47] op_sel_hi:[0,1]
	v_cvt_pk_bf16_f32 v150, v150, v151
	v_cvt_pk_bf16_f32 v151, v152, v153
	v_cvt_pk_bf16_f32 v152, v158, v159
	v_cvt_pk_bf16_f32 v153, v156, v157
	global_store_dwordx4 v149, v[150:153], s[98:99]
	s_nop 1
	v_pk_mul_f32 v[150:151], v[140:141], v[12:13] op_sel_hi:[0,1]
	v_pk_mul_f32 v[152:153], v[140:141], v[14:15] op_sel_hi:[0,1]
	v_cvt_pk_bf16_f32 v150, v150, v151
	v_cvt_pk_bf16_f32 v151, v152, v153
	v_pk_mul_f32 v[156:157], v[140:141], v[10:11] op_sel_hi:[0,1]
	v_pk_mul_f32 v[158:159], v[140:141], v[8:9] op_sel_hi:[0,1]
	v_cvt_pk_bf16_f32 v152, v158, v159
	v_cvt_pk_bf16_f32 v153, v156, v157
	global_store_dwordx4 v149, v[150:153], s[98:99] offset:256
	s_add_u32 s98, s98, 0x14000
	s_addc_u32 s99, s99, 0
	v_pk_mul_f32 v[154:155], v[140:141], v[32:33] op_sel_hi:[0,1]
	s_and_b32 s36, s70, -2
	v_pk_mul_f32 v[144:145], v[140:141], v[38:39] op_sel_hi:[0,1]
	v_pk_mul_f32 v[142:143], v[140:141], v[36:37] op_sel_hi:[0,1]
	v_pk_mul_f32 v[152:153], v[140:141], v[34:35] op_sel_hi:[0,1]
	v_cvt_pk_bf16_f32 v142, v142, v143
	v_cvt_pk_bf16_f32 v143, v144, v145
	v_cvt_pk_bf16_f32 v144, v154, v155
	v_cvt_pk_bf16_f32 v145, v152, v153
	global_store_dwordx4 v149, v[142:145], s[98:99]
	s_cmp_lg_u32 s36, 2
	s_movk_i32 s84, 0x3000
	v_pk_mul_f32 v[144:145], v[140:141], v[6:7] op_sel_hi:[0,1]
	v_pk_mul_f32 v[142:143], v[140:141], v[4:5] op_sel_hi:[0,1]
	s_mov_b32 s92, 0x358637bd
	v_pk_mul_f32 v[152:153], v[140:141], v[2:3] op_sel_hi:[0,1]
	v_pk_mul_f32 v[154:155], v[140:141], v[0:1] op_sel_hi:[0,1]
	v_cvt_pk_bf16_f32 v142, v142, v143
	v_cvt_pk_bf16_f32 v143, v144, v145
	v_cvt_pk_bf16_f32 v144, v154, v155
	v_cvt_pk_bf16_f32 v145, v152, v153
	global_store_dwordx4 v149, v[142:145], s[98:99] offset:256
	s_cbranch_scc1 .LBB0_189
	v_mul_f32_e32 v125, v125, v125
	v_mul_f32_e32 v117, v117, v117
	v_fmac_f32_e32 v125, v124, v124
	v_mul_f32_e32 v124, v127, v127
	v_fmac_f32_e32 v117, v116, v116
	v_mul_f32_e32 v116, v119, v119
	v_mul_f32_e32 v109, v109, v109
	v_mul_f32_e32 v101, v101, v101
	v_fmac_f32_e32 v124, v126, v126
	v_mul_f32_e32 v121, v121, v121
	v_fmac_f32_e32 v116, v118, v118
	v_mul_f32_e32 v113, v113, v113
	v_fmac_f32_e32 v109, v108, v108
	v_mul_f32_e32 v108, v111, v111
	v_fmac_f32_e32 v101, v100, v100
	v_mul_f32_e32 v100, v103, v103
	v_add_f32_e32 v124, v125, v124
	v_fmac_f32_e32 v121, v120, v120
	v_add_f32_e32 v116, v117, v116
	v_fmac_f32_e32 v113, v112, v112
	v_fmac_f32_e32 v108, v110, v110
	v_mul_f32_e32 v105, v105, v105
	v_fmac_f32_e32 v100, v102, v102
	v_mul_f32_e32 v97, v97, v97
	v_cmp_lt_i32_e32 vcc, v218, v220
	v_add_f32_e32 v120, v124, v121
	v_mul_f32_e32 v121, v123, v123
	v_add_f32_e32 v112, v116, v113
	v_mul_f32_e32 v113, v115, v115
	v_add_f32_e32 v108, v109, v108
	v_fmac_f32_e32 v105, v104, v104
	v_add_f32_e32 v100, v101, v100
	v_fmac_f32_e32 v97, v96, v96
	v_cndmask_b32_e32 v140, v213, v218, vcc
	v_fmac_f32_e32 v121, v122, v122
	v_fmac_f32_e32 v113, v114, v114
	v_add_f32_e32 v104, v108, v105
	v_mul_f32_e32 v105, v107, v107
	v_add_f32_e32 v96, v100, v97
	v_mul_f32_e32 v97, v99, v99
	v_lshlrev_b32_e32 v140, 2, v140
	v_add_f32_e32 v122, v121, v120
	v_add_f32_e32 v112, v113, v112
	v_fmac_f32_e32 v105, v106, v106
	v_fmac_f32_e32 v97, v98, v98
	ds_bpermute_b32 v123, v140, v122
	ds_bpermute_b32 v113, v140, v112
	v_add_f32_e32 v104, v105, v104
	v_add_f32_e32 v96, v97, v96
	ds_bpermute_b32 v105, v140, v104
	ds_bpermute_b32 v97, v140, v96
	v_cmp_lt_i32_e32 vcc, v219, v220
	s_waitcnt lgkmcnt(0)
	v_add_f32_e32 v122, v122, v123
	v_add_f32_e32 v98, v112, v113
	v_cndmask_b32_e32 v142, v213, v219, vcc
	v_lshlrev_b32_e32 v121, 2, v142
	ds_bpermute_b32 v123, v121, v122
	ds_bpermute_b32 v99, v121, v98
	v_add_f32_e32 v100, v104, v105
	v_add_f32_e32 v96, v96, v97
	ds_bpermute_b32 v101, v121, v100
	ds_bpermute_b32 v97, v121, v96
	v_cmp_lt_i32_e32 vcc, v252, v220
	s_waitcnt lgkmcnt(0)
	v_add_f32_e32 v102, v122, v123
	v_add_f32_e32 v98, v98, v99
	v_cndmask_b32_e32 v120, v213, v252, vcc
	v_max3_f32 v98, v102, 0, v98
	v_add_f32_e32 v99, v100, v101
	v_add_f32_e32 v96, v96, v97
	v_lshlrev_b32_e32 v120, 2, v120
	v_max3_f32 v97, v98, v99, v96
	ds_bpermute_b32 v98, v120, v97
	v_cmp_lt_i32_e32 vcc, v227, v220
	s_waitcnt lgkmcnt(0)
	v_max_f32_e32 v98, v98, v98
	v_cndmask_b32_e32 v96, v213, v227, vcc
	v_lshlrev_b32_e32 v96, 2, v96
	v_max_f32_e32 v98, v97, v98
	ds_bpermute_b32 v99, v96, v98
	v_cmp_lt_i32_e32 vcc, v216, v220
	s_waitcnt lgkmcnt(0)
	v_max_f32_e32 v99, v99, v99
	v_cndmask_b32_e32 v97, v213, v216, vcc
	v_lshlrev_b32_e32 v97, 2, v97
	v_max_f32_e32 v99, v98, v99
	ds_bpermute_b32 v100, v97, v99
	v_cmp_lt_i32_e32 vcc, v217, v220
	s_waitcnt lgkmcnt(0)
	v_max_f32_e32 v100, v100, v100
	v_cndmask_b32_e32 v98, v213, v217, vcc
	v_lshlrev_b32_e32 v98, 2, v98
	v_max_f32_e32 v99, v99, v100
	ds_bpermute_b32 v100, v98, v99
	s_and_saveexec_b64 s[36:37], s[38:39]
	s_cbranch_execz .LBB0_173
	s_waitcnt lgkmcnt(0)
	v_max_f32_e32 v100, v100, v100
	v_max_f32_e32 v99, v99, v99
	s_mov_b64 s[58:59], exec
	v_max_f32_e32 v99, v99, v100
	s_mov_b32 s51, 0
